# r47 + 36 bytes of unreachable padding before the merge phase so the M3/M4/out-proj loops keep r45's code alignment (mod 64)
# speedup vs baseline: 1.0093x; 1.0093x over previous
.LBB0_967:
	v_ashrrev_i32_e32 v5, 3, v4
	s_lshl_b64 s[6:7], s[2:3], 11
	v_add_u32_e32 v6, 64, v5
	v_mov_b32_e32 v7, v0
	v_lshl_add_u64 v[6:7], s[6:7], 0, v[6:7]
	s_waitcnt vmcnt(2)
	v_mov_b64_e32 v[8:9], s[58:59]
	s_movk_i32 s8, 0x1e00
	v_mad_u64_u32 v[8:9], s[6:7], v6, s8, v[8:9]
	v_mad_i32_i24 v9, v7, s8, v9
	s_lshl_b32 s88, s30, 7
	v_lshlrev_b32_e32 v5, 4, v2
	v_lshl_add_u64 v[6:7], v[8:9], 0, s[88:89]
	v_and_b32_e32 v8, 0x70, v5
	v_mov_b32_e32 v9, v0
	v_lshl_add_u64 v[6:7], v[6:7], 0, v[8:9]
	global_load_dwordx4 v[140:143], v[6:7], off offset:1536
	s_or_b64 exec, exec, s[4:5]
	s_and_saveexec_b64 s[4:5], s[20:21]
	s_cbranch_execnz .LBB0_903
	s_branch .LBB0_904
	s_nop 0
	s_nop 0
	s_nop 0
	s_nop 0
	s_nop 0
	s_nop 0
	s_nop 0
	s_nop 0
	s_nop 0
